# v29 + SwiGLU epilogue inputs (row scales, bias) of the next unit requested one epilogue ahead, packed across the wave in v236..v240 and spread with ds_bpermute; first unit of a phase loads directly
# baseline (speedup 1.0000x reference)
; #define LAS __attribute__((address_space(3)))
;     __device__ __forceinline__ const float* in(int i) const { const unsigned long long lo = u(2 * i), hi = u(2 * i + 1); return (const float*)(const __attribute__((address_space(1))) float*)((hi << 32) | lo); }
;     __device__ __forceinline__ float* out() const { const unsigned long long lo = u(60), hi = u(61); return (float*)(__attribute__((address_space(1))) float*)((hi << 32) | lo); }
;     __device__ __forceinline__ unsigned char* ws() const { const unsigned long long lo = u(62), hi = u(63); return (unsigned char*)(__attribute__((address_space(1))) unsigned char*)((hi << 32) | lo); }
; __global__ void __launch_bounds__(NTHREADS, 2) mega_fwd(Params KP) {
;     extern __shared__ __attribute__((aligned(16))) unsigned char lds_raw[];
;     LAS unsigned char* lds = (LAS unsigned char*)lds_raw;
;     cg::grid_group grid = cg::this_grid();
;     { LAS unsigned* pd = (LAS unsigned*)(lds + 133376);
;       if (threadIdx.x == 0) { ((LAS unsigned*)(lds + 133888))[0] = 0u; ((LAS unsigned*)(lds + 133888))[1] = 0u;
; #pragma unroll
;           for (int i = 0; i < 30; ++i) { const unsigned long long a = (unsigned long long)(uintptr_t)KP.in[i]; pd[2 * i] = (unsigned)a; pd[2 * i + 1] = (unsigned)(a >> 32); }
;           { const unsigned long long a = (unsigned long long)(uintptr_t)KP.out; pd[60] = (unsigned)a; pd[61] = (unsigned)(a >> 32); }
;           { const unsigned long long a = (unsigned long long)(uintptr_t)KP.ws; pd[62] = (unsigned)a; pd[63] = (unsigned)(a >> 32); } }
;       __syncthreads(); }
;     const PL P{(const LAS unsigned*)(lds + 133376)};
_Z8mega_fwd6Params:
	v_writelane_b32 v250, 0, 62
	s_load_dwordx2 s[72:73], s[0:1], 0x108
	s_mov_b32 s70, s2
	s_add_u32 s2, s0, 0x108
	s_addc_u32 s3, s1, 0
	v_and_b32_e32 v216, 0x3ff, v0
	v_writelane_b32 v251, s2, 0
	v_cmp_eq_u32_e64 s[76:77], 0, v216
	v_cmp_ne_u32_e32 vcc, 0, v216
	v_writelane_b32 v251, s3, 1
	s_and_saveexec_b64 s[2:3], vcc
	s_xor_b64 s[2:3], exec, s[2:3]
	s_load_dwordx2 s[4:5], s[0:1], 0xf8
	s_or_saveexec_b64 s[2:3], s[2:3]
	s_load_dword s24, s[0:1], 0x110
	s_waitcnt lgkmcnt(0)
	v_mov_b64_e32 v[2:3], s[4:5]
	s_xor_b64 exec, exec, s[2:3]
	s_cbranch_execz .LBB0_4
	s_load_dwordx16 s[4:19], s[0:1], 0x0
	s_add_i32 s20, 0, 0x20b00
	v_mov_b32_e32 v2, 0
	v_mov_b32_e32 v3, v2
	v_mov_b32_e32 v1, s20
	ds_write_b64 v1, v[2:3]
	s_waitcnt lgkmcnt(0)
	v_mov_b32_e32 v2, s4
	s_add_i32 s4, 0, 0x20900
	s_load_dwordx16 s[36:51], s[0:1], 0x40
	v_mov_b32_e32 v3, s5
	v_mov_b32_e32 v4, s6
	v_mov_b32_e32 v5, s7
	v_mov_b32_e32 v1, s4
	s_add_i32 s4, 0, 0x20910
	ds_write_b128 v1, v[2:5]
	v_mov_b32_e32 v2, s8
	v_mov_b32_e32 v3, s9
	v_mov_b32_e32 v4, s10
	v_mov_b32_e32 v5, s11
	v_mov_b32_e32 v1, s4
	s_add_i32 s4, 0, 0x20920
	ds_write_b128 v1, v[2:5]
	v_mov_b32_e32 v2, s12
	v_mov_b32_e32 v3, s13
	v_mov_b32_e32 v4, s14
	v_mov_b32_e32 v5, s15
	v_mov_b32_e32 v1, s4
	s_add_i32 s4, 0, 0x20930
	ds_write_b128 v1, v[2:5]
	v_mov_b32_e32 v2, s16
	v_mov_b32_e32 v3, s17
	v_mov_b32_e32 v4, s18
	v_mov_b32_e32 v5, s19
	v_mov_b32_e32 v1, s4
	s_add_i32 s4, 0, 0x20940
	s_load_dwordx16 s[8:23], s[0:1], 0x80
	ds_write_b128 v1, v[2:5]
	s_waitcnt lgkmcnt(0)
	v_mov_b32_e32 v2, s36
	v_mov_b32_e32 v3, s37
	v_mov_b32_e32 v4, s38
	v_mov_b32_e32 v5, s39
	v_mov_b32_e32 v1, s4
	s_add_i32 s4, 0, 0x20950
	ds_write_b128 v1, v[2:5]
	v_mov_b32_e32 v2, s40
	v_mov_b32_e32 v3, s41
	v_mov_b32_e32 v4, s42
	v_mov_b32_e32 v5, s43
	v_mov_b32_e32 v1, s4
	s_add_i32 s4, 0, 0x20960
	ds_write_b128 v1, v[2:5]
	v_mov_b32_e32 v2, s44
	v_mov_b32_e32 v3, s45
	v_mov_b32_e32 v4, s46
	v_mov_b32_e32 v5, s47
	v_mov_b32_e32 v1, s4
	s_add_i32 s4, 0, 0x20970
	ds_write_b128 v1, v[2:5]
	v_mov_b32_e32 v2, s48
	v_mov_b32_e32 v3, s49
	v_mov_b32_e32 v4, s50
	v_mov_b32_e32 v5, s51
	v_mov_b32_e32 v1, s4
	s_add_i32 s4, 0, 0x20980
	ds_write_b128 v1, v[2:5]
	v_mov_b32_e32 v2, s8
	v_mov_b32_e32 v3, s9
	v_mov_b32_e32 v4, s10
	v_mov_b32_e32 v5, s11
	v_mov_b32_e32 v1, s4
	s_add_i32 s4, 0, 0x20990
	ds_write_b128 v1, v[2:5]
	v_mov_b32_e32 v2, s12
	v_mov_b32_e32 v3, s13
	v_mov_b32_e32 v4, s14
	v_mov_b32_e32 v5, s15
	v_mov_b32_e32 v1, s4
	s_add_i32 s4, 0, 0x209a0
	ds_write_b128 v1, v[2:5]
	v_mov_b32_e32 v2, s16
	v_mov_b32_e32 v3, s17
	v_mov_b32_e32 v4, s18
	v_mov_b32_e32 v5, s19
	v_mov_b32_e32 v1, s4
	s_load_dwordx16 s[4:19], s[0:1], 0xc0
	ds_write_b128 v1, v[2:5]
	v_mov_b32_e32 v2, s20
	s_add_i32 s20, 0, 0x209b0
	v_mov_b32_e32 v3, s21
	v_mov_b32_e32 v4, s22
	v_mov_b32_e32 v5, s23
	v_mov_b32_e32 v1, s20
	ds_write_b128 v1, v[2:5]
	s_waitcnt lgkmcnt(0)
	v_mov_b32_e32 v2, s4
	s_add_i32 s4, 0, 0x209c0
	v_mov_b32_e32 v3, s5
	v_mov_b32_e32 v4, s6
	v_mov_b32_e32 v5, s7
	v_mov_b32_e32 v1, s4
	s_add_i32 s4, 0, 0x209d0
	ds_write_b128 v1, v[2:5]
	v_mov_b32_e32 v2, s8
	v_mov_b32_e32 v3, s9
	v_mov_b32_e32 v4, s10
	v_mov_b32_e32 v5, s11
	v_mov_b32_e32 v1, s4
	s_add_i32 s4, 0, 0x209e0
	ds_write_b128 v1, v[2:5]
	v_mov_b32_e32 v2, s12
	v_mov_b32_e32 v3, s13
	v_mov_b32_e32 v4, s14
	v_mov_b32_e32 v5, s15
	v_mov_b32_e32 v1, s4
	s_add_i32 s4, 0, 0x209f0
	ds_write_b128 v1, v[2:5]
	v_mov_b32_e32 v2, s16
	v_mov_b32_e32 v3, s17
	v_mov_b32_e32 v4, s18
	v_mov_b32_e32 v5, s19
	v_mov_b32_e32 v1, s4
	ds_write_b128 v1, v[2:5]
	v_mov_b64_e32 v[2:3], s[18:19]

;     __device__ __forceinline__ unsigned u(int i) const { return (unsigned)__builtin_amdgcn_readfirstlane((int)d[i]); }
;     template <class T> __device__ __forceinline__ T* p(int i) const { const unsigned long long lo = u(i), hi = u(i + 1); return (T*)(__attribute__((address_space(1))) T*)((hi << 32) | lo); }
;     __device__ __forceinline__ unsigned u(int i) const { return (unsigned)__builtin_amdgcn_readfirstlane((int)d[i]); }
;     static __device__ __forceinline__ void run(const f32x4 (&acc)[2][2][4][2], const Unit& u, int wr, int wc, int fr, int fq, bf16_t* H, int ldh, const float* ssqA, const float* ssqB, const float* bvec) {
;         const int b = (u.pm * BM) >> 13; const int row0 = u.pm * BM + wr * 64 + fr; const int col0 = u.pn * 128 + wc * 32 + 8 * fq;
;         const float* bp = bvec + ((unsigned)b * (unsigned)(2 * ldh) + (unsigned)(u.pn * BM + wc * 32 + 8 * fq));
;         const f32x4 bg0 = *(const f32x4*)bp * 1.4426950408889634f, bg1 = *(const f32x4*)(bp + 4) * 1.4426950408889634f, bu0 = *(const f32x4*)(bp + HALF) * 0.6931471805599453f, bu1 = *(const f32x4*)(bp + HALF + 4) * 0.6931471805599453f;
;     ...
; #pragma unroll
;         for (int ai = 0; ai < 2; ++ai)
; #pragma unroll
;             for (int m = 0; m < 4; ++m) {
;                 const int row = row0 + ai * HALF + m * 16; const float r = row_scale(ssqA, ssqB, row); const float rg = r * 1.4426950408889634f, ru = r * 0.6931471805599453f;
;                 bf16_t* p = H + ((unsigned)row * (unsigned)ldh + (unsigned)col0);
.LBB0_546:
	s_andn2_b64 vcc, exec, s[26:27]
	s_cbranch_vccnz .LBB0_564
	v_mov_b32_e32 v128, 0x20804
	ds_read_b32 v128, v128
	v_mov_b32_e32 v130, 0x20810
	ds_read_b64 v[130:131], v130
	v_mov_b32_e32 v132, 0x20838
	ds_read_b128 v[132:135], v132
	v_mov_b32_e32 v136, 0x20848
	ds_read_b64 v[136:137], v136
	s_waitcnt lgkmcnt(0)
	v_readfirstlane_b32 s26, v128
	v_readfirstlane_b32 s2, v132
	v_readfirstlane_b32 s3, v133
	v_readfirstlane_b32 s28, v134
	v_readfirstlane_b32 s29, v135
	v_readfirstlane_b32 s8, v136
	v_readfirstlane_b32 s9, v137
	v_readfirstlane_b32 s10, v130
	v_readfirstlane_b32 s11, v131
	s_lshl_b32 s27, s63, 8
	s_lshl_b32 vcc_lo, s65, 6
	s_add_i32 s27, s27, vcc_lo
	v_or_b32_e32 v143, s27, v230
	s_lshl_b32 vcc_lo, s62, 7
	s_lshl_b32 vcc_hi, s64, 5
	s_add_i32 vcc_lo, vcc_lo, vcc_hi
	v_lshl_add_u32 v150, v229, 3, vcc_lo
	v_mul_lo_u32 v151, s26, v143
	v_add_u32_e32 v150, v151, v150
	v_lshlrev_b32_e32 v150, 1, v150
	v_mov_b32_e32 v151, 0
	v_lshl_add_u64 v[156:157], s[10:11], 0, v[150:151]
	v_readlane_b32 s27, v250, 62
	s_cmp_eq_u32 s27, 0
	s_cbranch_scc1 .Lswg_direct
	v_lshlrev_b32_e32 v128, 2, v230
	v_add_u32_e32 v129, 64, v128
	v_add_u32_e32 v130, 0x80, v128
	v_add_u32_e32 v131, 0xc0, v128
	ds_bpermute_b32 v172, v128, v237
	ds_bpermute_b32 v173, v128, v238
	ds_bpermute_b32 v174, v129, v237
	ds_bpermute_b32 v175, v129, v238
	ds_bpermute_b32 v180, v130, v237
	ds_bpermute_b32 v181, v130, v238
	ds_bpermute_b32 v182, v131, v237
	ds_bpermute_b32 v183, v131, v238
	s_cmp_eq_u64 s[28:29], 0
	s_cbranch_scc1 .Lswg_xnob
	ds_bpermute_b32 v200, v128, v239
	ds_bpermute_b32 v201, v128, v240
	ds_bpermute_b32 v202, v129, v239
	ds_bpermute_b32 v203, v129, v240
	ds_bpermute_b32 v204, v130, v239
	ds_bpermute_b32 v205, v130, v240
	ds_bpermute_b32 v206, v131, v239
	ds_bpermute_b32 v207, v131, v240
.Lswg_xnob:
	v_lshlrev_b32_e32 v132, 6, v229
	v_add_u32_e32 v133, 4, v132
	ds_bpermute_b32 v184, v132, v236
	v_add_u32_e32 v132, 8, v132
	ds_bpermute_b32 v185, v133, v236
	v_add_u32_e32 v133, 8, v133
	ds_bpermute_b32 v186, v132, v236
	v_add_u32_e32 v132, 8, v132
	ds_bpermute_b32 v187, v133, v236
	v_add_u32_e32 v133, 8, v133
	ds_bpermute_b32 v188, v132, v236
	v_add_u32_e32 v132, 8, v132
	ds_bpermute_b32 v189, v133, v236
	v_add_u32_e32 v133, 8, v133
	ds_bpermute_b32 v190, v132, v236
	v_add_u32_e32 v132, 8, v132
	ds_bpermute_b32 v191, v133, v236
	v_add_u32_e32 v133, 8, v133
	ds_bpermute_b32 v192, v132, v236
	v_add_u32_e32 v132, 8, v132
	ds_bpermute_b32 v193, v133, v236
	v_add_u32_e32 v133, 8, v133
	ds_bpermute_b32 v194, v132, v236
	v_add_u32_e32 v132, 8, v132
	ds_bpermute_b32 v195, v133, v236
	v_add_u32_e32 v133, 8, v133
	ds_bpermute_b32 v196, v132, v236
	v_add_u32_e32 v132, 8, v132
	ds_bpermute_b32 v197, v133, v236
	v_add_u32_e32 v133, 8, v133
	ds_bpermute_b32 v198, v132, v236
	ds_bpermute_b32 v199, v133, v236
	s_waitcnt lgkmcnt(0)
	s_branch .Lswg_loaded
.Lswg_direct:
	v_lshlrev_b32_e32 v144, 2, v143
	v_mov_b32_e32 v145, 0
	v_lshl_add_u64 v[146:147], s[28:29], 0, v[144:145]
	v_lshl_add_u64 v[144:145], s[2:3], 0, v[144:145]
	global_load_dword v172, v[144:145], off
	global_load_dword v173, v[144:145], off offset:64
	global_load_dword v174, v[144:145], off offset:128
	global_load_dword v175, v[144:145], off offset:192
	global_load_dword v180, v[144:145], off offset:512
	global_load_dword v181, v[144:145], off offset:576
	global_load_dword v182, v[144:145], off offset:640
	global_load_dword v183, v[144:145], off offset:704
	s_lshr_b32 vcc_lo, s63, 5
	s_lshl_b32 vcc_lo, vcc_lo, 1
	s_mul_i32 vcc_lo, vcc_lo, s26
	s_lshl_b32 vcc_hi, s62, 8
	s_add_i32 vcc_lo, vcc_lo, vcc_hi
	s_lshl_b32 vcc_hi, s64, 5
	s_add_i32 vcc_lo, vcc_lo, vcc_hi
	v_lshl_add_u32 v148, v229, 3, vcc_lo
	v_lshlrev_b32_e32 v148, 2, v148
	v_mov_b32_e32 v149, 0
	v_lshl_add_u64 v[148:149], s[8:9], 0, v[148:149]
	global_load_dwordx4 v[184:187], v[148:149], off
	global_load_dwordx4 v[188:191], v[148:149], off offset:16
	global_load_dwordx4 v[192:195], v[148:149], off offset:512
	global_load_dwordx4 v[196:199], v[148:149], off offset:528
	s_cmp_eq_u64 s[28:29], 0
	s_cbranch_scc1 .Lswg_nob
	global_load_dword v200, v[146:147], off
	global_load_dword v201, v[146:147], off offset:64
	global_load_dword v202, v[146:147], off offset:128
	global_load_dword v203, v[146:147], off offset:192
	global_load_dword v204, v[146:147], off offset:512
	global_load_dword v205, v[146:147], off offset:576
	global_load_dword v206, v[146:147], off offset:640
	global_load_dword v207, v[146:147], off offset:704

;     __device__ __forceinline__ unsigned u(int i) const { return (unsigned)__builtin_amdgcn_readfirstlane((int)d[i]); }
;     __device__ __forceinline__ unsigned u(int i) const { return (unsigned)__builtin_amdgcn_readfirstlane((int)d[i]); }
;     static __device__ __forceinline__ void run(const f32x4 (&acc)[2][2][4][2], const Unit& u, int wr, int wc, int fr, int fq, bf16_t* H, int ldh, const float* ssqA, const float* ssqB, const float* bvec) {
;         const int b = (u.pm * BM) >> 13; const int row0 = u.pm * BM + wr * 64 + fr; const int col0 = u.pn * 128 + wc * 32 + 8 * fq;
;         const float* bp = bvec + ((unsigned)b * (unsigned)(2 * ldh) + (unsigned)(u.pn * BM + wc * 32 + 8 * fq));
;         const f32x4 bg0 = *(const f32x4*)bp * 1.4426950408889634f, bg1 = *(const f32x4*)(bp + 4) * 1.4426950408889634f, bu0 = *(const f32x4*)(bp + HALF) * 0.6931471805599453f, bu1 = *(const f32x4*)(bp + HALF + 4) * 0.6931471805599453f;
;     ...
; #pragma unroll
;         for (int ai = 0; ai < 2; ++ai)
; #pragma unroll
;             for (int m = 0; m < 4; ++m) {
;                 const int row = row0 + ai * HALF + m * 16; const float r = row_scale(ssqA, ssqB, row); const float rg = r * 1.4426950408889634f, ru = r * 0.6931471805599453f;
.Lswg_loaded:
	s_cmp_eq_u64 s[6:7], 0
	s_cbranch_scc0 .Lswg_nopf
	s_lshl_b32 s27, s61, 8
	s_lshl_b32 vcc_lo, s65, 6
	s_add_i32 s27, s27, vcc_lo
	v_lshrrev_b32_e32 v128, 1, v229
	v_lshlrev_b32_e32 v128, 7, v128
	v_and_b32_e32 v129, 1, v229
	v_lshl_add_u32 v128, v129, 5, v128
	v_add3_u32 v128, v128, v230, s27
	v_lshlrev_b32_e32 v128, 2, v128
	v_mov_b32_e32 v129, 0
	v_lshl_add_u64 v[130:131], s[2:3], 0, v[128:129]
	global_load_dword v237, v[130:131], off
	global_load_dword v238, v[130:131], off offset:64
	s_cmp_eq_u64 s[28:29], 0
	s_cbranch_scc1 .Lswg_pnob
	v_lshl_add_u64 v[130:131], s[28:29], 0, v[128:129]
	global_load_dword v239, v[130:131], off
	global_load_dword v240, v[130:131], off offset:64
.Lswg_pnob:
	s_lshr_b32 vcc_lo, s61, 5
	s_lshl_b32 vcc_lo, vcc_lo, 1
	s_mul_i32 vcc_lo, vcc_lo, s26
	s_lshl_b32 vcc_hi, s60, 8
	s_add_i32 vcc_lo, vcc_lo, vcc_hi
	s_lshl_b32 vcc_hi, s64, 5
	s_add_i32 vcc_lo, vcc_lo, vcc_hi
	v_and_b32_e32 v132, 7, v230
	v_lshrrev_b32_e32 v133, 3, v230
	v_lshl_add_u32 v132, v133, 7, v132
	v_lshl_add_u32 v132, v229, 3, v132
	v_add_u32_e32 v132, vcc_lo, v132
	v_lshlrev_b32_e32 v132, 2, v132
	v_mov_b32_e32 v133, 0
	v_lshl_add_u64 v[132:133], s[8:9], 0, v[132:133]
	global_load_dword v236, v[132:133], off
	s_mov_b32 s27, 1
	s_branch .Lswg_pfdone
.Lswg_nopf:
	s_mov_b32 s27, 0
.Lswg_pfdone:
	v_writelane_b32 v250, s27, 62
	s_mov_b32 s8, 0x3fb8aa3b
	s_mov_b32 s10, 0x3f317218
	v_pk_mul_f32 v[184:185], v[184:185], s[8:9] op_sel_hi:[1,0]
	v_pk_mul_f32 v[186:187], v[186:187], s[8:9] op_sel_hi:[1,0]
	v_pk_mul_f32 v[192:193], v[192:193], s[10:11] op_sel_hi:[1,0]
	v_pk_mul_f32 v[194:195], v[194:195], s[10:11] op_sel_hi:[1,0]
	v_pk_mul_f32 v[188:189], v[188:189], s[8:9] op_sel_hi:[1,0]
	v_pk_mul_f32 v[190:191], v[190:191], s[8:9] op_sel_hi:[1,0]
	v_pk_mul_f32 v[196:197], v[196:197], s[10:11] op_sel_hi:[1,0]
	v_pk_mul_f32 v[198:199], v[198:199], s[10:11] op_sel_hi:[1,0]
	v_fmamk_f32 v152, v172, 0x3a800000, v222
	v_rsq_f32_e32 v152, v152
	s_cmp_eq_u64 s[28:29], 0
	s_cbranch_scc1 .Lswg_r0
	v_mul_f32_e32 v153, v152, v152
	v_mul_f32_e32 v153, v153, v200
	v_fmamk_f32 v153, v153, 0x3a800000, v222
	v_rsq_f32_e32 v153, v153
	s_nop 0
	v_mul_f32_e32 v152, v152, v153
